# k27 + pooling-phase rope section: the 16 loads of its four passes issued together up front
# speedup vs baseline: 1.0025x; 1.0025x over previous
; __device__ __forceinline__ unsigned cvt_pk_bf16(float lo, float hi) { unsigned r; asm volatile("v_cvt_pk_bf16_f32 %0, %1, %2" : "=v"(r) : "v"(lo), "v"(hi)); return r; }
; #define GASF __attribute__((address_space(1)))
; __device__ __forceinline__ void pool_rows(const bf16_t* Z_, bf16_t* DIFF_, float* RQ_, float* RKV_, bf16_t* Kb_, const float* cs_, const float* sn_, int SEQ, int gw, int NGW, int lane) {
;     ...
;           for (int ps = 0; ps < 4; ++ps) { const int t = t0 + ps * 4 + tok, s = t & (SEQ - 1), i = sub; const GASF bf16_t* zr = Z + (size_t)t * INP + Z_KR;
;               const float x1 = __uint_as_float((unsigned)zr[i] << 16), x2 = __uint_as_float((unsigned)zr[i + 16] << 16); const float c = cs[s * 16 + i], sv = sn[s * 16 + i];
;               const unsigned w = cvt_pk_bf16(x1 * c - x2 * sv, x2 * c + x1 * sv);
; #pragma unroll
;               for (int h = 0; h < NH; ++h) *(GASF unsigned*)(Kb + (size_t)t * QW + h * QKD + 64 + 2 * i) = w; } }
.LBB0_367:
	s_or_b64 exec, exec, s[18:19]
	v_lshlrev_b32_e32 v174, 1, v32
	v_lshl_add_u64 v[2:3], v[2:3], 0, v[174:175]
	v_lshl_add_u64 v[100:101], v[6:7], 0, v[174:175]
	v_lshl_add_u64 v[102:103], v[10:11], 0, v[174:175]
	v_lshl_add_u64 v[104:105], v[12:13], 0, v[174:175]
	global_load_ushort v88, v[2:3], off offset:2304
	global_load_ushort v89, v[2:3], off offset:2336
	global_load_ushort v90, v[100:101], off offset:2304
	global_load_ushort v91, v[100:101], off offset:2336
	global_load_ushort v92, v[102:103], off offset:2304
	global_load_ushort v93, v[102:103], off offset:2336
	global_load_ushort v94, v[104:105], off offset:2304
	global_load_ushort v95, v[104:105], off offset:2336
	v_and_b32_e32 v106, s9, v0
	v_lshl_or_b32 v106, v106, 4, v32
	v_mov_b32_e32 v107, v175
	v_lshlrev_b64 v[106:107], 2, v[106:107]
	v_lshl_add_u64 v[108:109], s[14:15], 0, v[106:107]
	v_lshl_add_u64 v[106:107], s[16:17], 0, v[106:107]
	global_load_dword v96, v[108:109], off
	global_load_dword v97, v[106:107], off
	v_and_b32_e32 v106, s9, v1
	v_lshl_or_b32 v106, v106, 4, v32
	v_mov_b32_e32 v107, v175
	v_lshlrev_b64 v[106:107], 2, v[106:107]
	v_lshl_add_u64 v[108:109], s[14:15], 0, v[106:107]
	v_lshl_add_u64 v[106:107], s[16:17], 0, v[106:107]
	global_load_dword v98, v[108:109], off
	global_load_dword v99, v[106:107], off
	v_and_b32_e32 v106, s9, v14
	v_lshl_or_b32 v106, v106, 4, v32
	v_mov_b32_e32 v107, v175
	v_lshlrev_b64 v[106:107], 2, v[106:107]
	v_lshl_add_u64 v[108:109], s[14:15], 0, v[106:107]
	v_lshl_add_u64 v[106:107], s[16:17], 0, v[106:107]
	global_load_dword v100, v[108:109], off
	global_load_dword v101, v[106:107], off
	v_and_b32_e32 v106, s9, v15
	v_lshl_or_b32 v106, v106, 4, v32
	v_mov_b32_e32 v107, v175
	v_lshlrev_b64 v[106:107], 2, v[106:107]
	v_lshl_add_u64 v[108:109], s[14:15], 0, v[106:107]
	v_lshl_add_u64 v[106:107], s[16:17], 0, v[106:107]
	global_load_dword v102, v[108:109], off
	global_load_dword v103, v[106:107], off
	s_waitcnt vmcnt(0)
	v_mov_b32_e32 v5, v88
	v_and_b32_e32 v4, s9, v0
	v_mov_b32_e32 v2, v89
	v_mov_b32_e32 v3, v175
	s_add_i32 s5, s5, s7
	s_add_i32 s8, s8, s10
	s_cmpk_lt_i32 s5, 0x800
	s_waitcnt vmcnt(1)
	v_lshlrev_b32_e32 v8, 16, v5
	s_waitcnt vmcnt(0)
	v_lshlrev_b32_e32 v9, 16, v2
	v_lshl_or_b32 v2, v4, 4, v32
	v_lshlrev_b64 v[2:3], 2, v[2:3]
	v_lshl_add_u64 v[4:5], s[14:15], 0, v[2:3]
	v_lshl_add_u64 v[2:3], s[16:17], 0, v[2:3]
	v_mov_b32_e32 v4, v96
	s_nop 0
	v_mov_b32_e32 v2, v97
	s_waitcnt vmcnt(0)
	v_mul_f32_e32 v3, v2, v9
	v_fma_f32 v3, v4, v8, -v3
	v_mul_f32_e32 v4, v4, v9
	v_fmac_f32_e32 v4, v2, v8
	v_cvt_pk_bf16_f32 v4, v3, v4
	v_mad_i64_i32 v[2:3], s[18:19], v0, s95, v[38:39]
	global_store_dword v[2:3], v4, off offset:128
	global_store_dword v[2:3], v4, off offset:320
	global_store_dword v[2:3], v4, off offset:512
	global_store_dword v[2:3], v4, off offset:704
	global_store_dword v[2:3], v4, off offset:896
	global_store_dword v[2:3], v4, off offset:1088
	global_store_dword v[2:3], v4, off offset:1280
	global_store_dword v[2:3], v4, off offset:1472
	v_lshl_add_u64 v[2:3], v[6:7], 0, v[174:175]
	v_mov_b32_e32 v4, v90
	v_and_b32_e32 v0, s9, v1
	v_mov_b32_e32 v2, v91
	v_mov_b32_e32 v3, v175
	s_waitcnt vmcnt(1)
	v_lshlrev_b32_e32 v6, 16, v4
	s_waitcnt vmcnt(0)
	v_lshlrev_b32_e32 v7, 16, v2
	v_lshl_or_b32 v2, v0, 4, v32
	v_lshlrev_b64 v[2:3], 2, v[2:3]
	v_lshl_add_u64 v[4:5], s[14:15], 0, v[2:3]
	v_lshl_add_u64 v[2:3], s[16:17], 0, v[2:3]
	v_mov_b32_e32 v0, v98
	s_nop 0
	v_mov_b32_e32 v2, v99
	s_waitcnt vmcnt(0)
	v_mul_f32_e32 v3, v2, v7
	v_fma_f32 v3, v0, v6, -v3
	v_mul_f32_e32 v0, v0, v7
	v_fmac_f32_e32 v0, v2, v6
	v_cvt_pk_bf16_f32 v2, v3, v0
	v_mad_i64_i32 v[0:1], s[18:19], v1, s95, v[38:39]
	global_store_dword v[0:1], v2, off offset:128
	global_store_dword v[0:1], v2, off offset:320
	global_store_dword v[0:1], v2, off offset:512
	global_store_dword v[0:1], v2, off offset:704
	global_store_dword v[0:1], v2, off offset:896
	global_store_dword v[0:1], v2, off offset:1088
	global_store_dword v[0:1], v2, off offset:1280
	global_store_dword v[0:1], v2, off offset:1472
	v_lshl_add_u64 v[0:1], v[10:11], 0, v[174:175]
	v_mov_b32_e32 v3, v92
	v_and_b32_e32 v2, s9, v14
	v_mov_b32_e32 v0, v93
	v_mov_b32_e32 v1, v175
	s_waitcnt vmcnt(1)
	v_lshlrev_b32_e32 v4, 16, v3
	s_waitcnt vmcnt(0)
	v_lshlrev_b32_e32 v5, 16, v0
	v_lshl_or_b32 v0, v2, 4, v32
	v_lshlrev_b64 v[0:1], 2, v[0:1]
	v_lshl_add_u64 v[2:3], s[14:15], 0, v[0:1]
	v_lshl_add_u64 v[0:1], s[16:17], 0, v[0:1]
	v_mov_b32_e32 v2, v100
	s_nop 0
	v_mov_b32_e32 v0, v101
	s_waitcnt vmcnt(0)
	v_mul_f32_e32 v1, v0, v5
	v_fma_f32 v1, v2, v4, -v1
	v_mul_f32_e32 v2, v2, v5
	v_fmac_f32_e32 v2, v0, v4
	v_cvt_pk_bf16_f32 v2, v1, v2
	v_mad_i64_i32 v[0:1], s[18:19], v14, s95, v[38:39]
	global_store_dword v[0:1], v2, off offset:128
	global_store_dword v[0:1], v2, off offset:320
	global_store_dword v[0:1], v2, off offset:512
	global_store_dword v[0:1], v2, off offset:704
	global_store_dword v[0:1], v2, off offset:896
	global_store_dword v[0:1], v2, off offset:1088
	global_store_dword v[0:1], v2, off offset:1280
	global_store_dword v[0:1], v2, off offset:1472
	v_lshl_add_u64 v[0:1], v[12:13], 0, v[174:175]
	v_mov_b32_e32 v3, v94
	v_and_b32_e32 v2, s9, v15
	v_mov_b32_e32 v0, v95
	v_lshl_or_b32 v174, v2, 4, v32
	s_waitcnt vmcnt(1)
	v_lshlrev_b32_e32 v4, 16, v3
	s_waitcnt vmcnt(0)
	v_lshlrev_b32_e32 v5, 16, v0
	v_lshlrev_b64 v[0:1], 2, v[174:175]
	v_lshl_add_u64 v[2:3], s[14:15], 0, v[0:1]
	v_lshl_add_u64 v[0:1], s[16:17], 0, v[0:1]
	v_mov_b32_e32 v2, v102
	s_nop 0
	v_mov_b32_e32 v0, v103
	s_waitcnt vmcnt(0)
	v_mul_f32_e32 v1, v0, v5
	v_fma_f32 v1, v2, v4, -v1
	v_mul_f32_e32 v2, v2, v5
	v_fmac_f32_e32 v2, v0, v4
	v_cvt_pk_bf16_f32 v2, v1, v2
	v_mad_i64_i32 v[0:1], s[18:19], v15, s95, v[38:39]
	global_store_dword v[0:1], v2, off offset:128
	global_store_dword v[0:1], v2, off offset:320
	global_store_dword v[0:1], v2, off offset:512
	global_store_dword v[0:1], v2, off offset:704
	global_store_dword v[0:1], v2, off offset:896
	global_store_dword v[0:1], v2, off offset:1088
	global_store_dword v[0:1], v2, off offset:1280
	global_store_dword v[0:1], v2, off offset:1472
	s_cbranch_scc0 .LBB0_394
